# GEMM K-loops P2/P5/P9: first iteration of each non-first tile no longer waits for the previous epilogue stores in its two leading DMA waits (vmcnt relaxed by the epilogue store count)
# speedup vs baseline: 1.0059x; 1.0026x over previous
.LBB0_213:
	s_add_u32 s20, s18, 0xfffc0080
	s_addc_u32 s21, s19, -1
	s_add_i32 s48, 0, 0x10000
	s_cmp_eq_u32 s46, 12
	s_cselect_b32 s23, s11, s21
	s_cselect_b32 s22, s42, s20
	s_cselect_b32 s21, s9, s45
	s_cselect_b32 s20, s43, s44
	s_add_i32 s50, 0, 0x14000
	v_add_u32_e32 v156, s48, v141
	v_add_u32_e32 v172, s50, v141
	ds_read_b128 v[144:147], v156
	ds_read_b128 v[148:151], v156 offset:1024
	ds_read_b128 v[152:155], v156 offset:2048
	ds_read_b128 v[156:159], v156 offset:3072
	ds_read_b128 v[160:163], v172
	ds_read_b128 v[164:167], v172 offset:1024
	ds_read_b128 v[168:171], v172 offset:2048
	ds_read_b128 v[172:175], v172 offset:3072
	v_lshl_add_u64 v[180:181], s[18:19], 0, v[136:137]
	s_add_i32 m0, s29, 0xc000
	ds_read_b128 v[176:179], v143
	ds_read_b128 v[186:189], v143 offset:1024
	ds_read_b128 v[190:193], v143 offset:2048
	ds_read_b128 v[212:215], v143 offset:3072
	ds_read_b128 v[216:219], v143 offset:4096
	ds_read_b128 v[220:223], v143 offset:5120
	ds_read_b128 v[224:227], v143 offset:6144
	ds_read_b128 v[228:231], v143 offset:7168
	global_load_lds_dwordx4 v[180:181], off
	v_lshl_add_u64 v[180:181], s[18:19], 0, v[138:139]
	s_add_i32 m0, s29, 0xe000
	s_nop 0
	global_load_lds_dwordx4 v[180:181], off
	s_cmp_eq_u32 s46, -2
	s_cselect_b32 s98, s37, 0
	s_cmp_gt_u32 s98, 1
	s_cbranch_scc1 .Ltw_relax_213_0
	s_waitcnt vmcnt(8)
	s_branch .Ltw_join_213_0
.Ltw_relax_213_0:
	s_waitcnt vmcnt(24)
.Ltw_join_213_0:
	s_waitcnt lgkmcnt(0)
	s_barrier
	s_setprio 1
	s_waitcnt lgkmcnt(0)
	v_mfma_f32_16x16x32_bf16 v[126:129], v[144:147], v[176:179], v[126:129]
	v_mfma_f32_16x16x32_bf16 v[122:125], v[152:155], v[176:179], v[122:125]
	v_mfma_f32_16x16x32_bf16 v[118:121], v[144:147], v[190:193], v[118:121]
	v_mfma_f32_16x16x32_bf16 v[114:117], v[152:155], v[190:193], v[114:117]
	v_mfma_f32_16x16x32_bf16 v[102:105], v[144:147], v[216:219], v[102:105]
	v_mfma_f32_16x16x32_bf16 v[98:101], v[152:155], v[216:219], v[98:101]
	v_mfma_f32_16x16x32_bf16 v[86:89], v[144:147], v[224:227], v[86:89]
	v_mfma_f32_16x16x32_bf16 v[82:85], v[152:155], v[224:227], v[82:85]
	v_mfma_f32_16x16x32_bf16 v[126:129], v[148:151], v[186:189], v[126:129]
	v_mfma_f32_16x16x32_bf16 v[122:125], v[156:159], v[186:189], v[122:125]
	v_mfma_f32_16x16x32_bf16 v[118:121], v[148:151], v[212:215], v[118:121]
	v_mfma_f32_16x16x32_bf16 v[114:117], v[156:159], v[212:215], v[114:117]
	v_mfma_f32_16x16x32_bf16 v[102:105], v[148:151], v[220:223], v[102:105]
	v_mfma_f32_16x16x32_bf16 v[98:101], v[156:159], v[220:223], v[98:101]
	v_mfma_f32_16x16x32_bf16 v[86:89], v[148:151], v[228:231], v[86:89]
	v_mfma_f32_16x16x32_bf16 v[82:85], v[156:159], v[228:231], v[82:85]
	s_setprio 0
	s_setprio 1
	v_mfma_f32_16x16x32_bf16 v[110:113], v[160:163], v[176:179], v[110:113]
	v_mfma_f32_16x16x32_bf16 v[106:109], v[168:171], v[176:179], v[106:109]
	v_mfma_f32_16x16x32_bf16 v[94:97], v[160:163], v[190:193], v[94:97]
	v_mfma_f32_16x16x32_bf16 v[90:93], v[168:171], v[190:193], v[90:93]
	v_mfma_f32_16x16x32_bf16 v[78:81], v[160:163], v[216:219], v[78:81]
	v_mfma_f32_16x16x32_bf16 v[74:77], v[168:171], v[216:219], v[74:77]
	v_mfma_f32_16x16x32_bf16 v[70:73], v[160:163], v[224:227], v[70:73]
	v_mfma_f32_16x16x32_bf16 v[66:69], v[168:171], v[224:227], v[66:69]
	v_mfma_f32_16x16x32_bf16 v[110:113], v[164:167], v[186:189], v[110:113]
	v_mfma_f32_16x16x32_bf16 v[106:109], v[172:175], v[186:189], v[106:109]
	v_mfma_f32_16x16x32_bf16 v[94:97], v[164:167], v[212:215], v[94:97]
	v_mfma_f32_16x16x32_bf16 v[90:93], v[172:175], v[212:215], v[90:93]
	v_mfma_f32_16x16x32_bf16 v[78:81], v[164:167], v[220:223], v[78:81]
	v_mfma_f32_16x16x32_bf16 v[74:77], v[172:175], v[220:223], v[74:77]
	v_mfma_f32_16x16x32_bf16 v[70:73], v[164:167], v[228:231], v[70:73]
	v_mfma_f32_16x16x32_bf16 v[66:69], v[172:175], v[228:231], v[66:69]
	s_setprio 0
	s_barrier
	s_add_i32 s48, s48, s28
	v_lshl_add_u64 v[180:181], s[20:21], 0, v[0:1]
	s_mov_b32 m0, s48
	ds_read_b128 v[176:179], v143 offset:16384
	ds_read_b128 v[186:189], v143 offset:17408
	ds_read_b128 v[190:193], v143 offset:18432
	ds_read_b128 v[212:215], v143 offset:19456
	ds_read_b128 v[216:219], v143 offset:20480
	ds_read_b128 v[220:223], v143 offset:21504
	ds_read_b128 v[224:227], v143 offset:22528
	ds_read_b128 v[228:231], v143 offset:23552
	global_load_lds_dwordx4 v[180:181], off
	s_add_i32 m0, s48, 0x2000
	s_add_u32 s48, s20, 0x40000
	v_lshl_add_u64 v[194:195], s[20:21], 0, v[130:131]
	s_addc_u32 s49, s21, 0
	s_add_i32 s50, s50, s28
	global_load_lds_dwordx4 v[194:195], off
	v_lshl_add_u64 v[232:233], s[48:49], 0, v[0:1]
	s_mov_b32 m0, s50
	v_lshl_add_u64 v[234:235], s[22:23], 0, v[132:133]
	global_load_lds_dwordx4 v[232:233], off
	v_lshl_add_u64 v[232:233], s[48:49], 0, v[130:131]
	s_add_i32 m0, s50, 0x2000
	s_nop 0
	global_load_lds_dwordx4 v[232:233], off
	v_lshl_add_u64 v[232:233], s[22:23], 0, v[134:135]
	s_mov_b32 m0, s29
	s_nop 0
	global_load_lds_dwordx4 v[232:233], off
	s_mov_b32 m0, s30
	s_nop 0
	global_load_lds_dwordx4 v[234:235], off
	s_cmp_eq_u32 s46, -2
	s_cselect_b32 s98, s37, 0
	s_cmp_gt_u32 s98, 1
	s_cbranch_scc1 .Ltw_relax_213_1
	s_waitcnt vmcnt(8)
	s_branch .Ltw_join_213_1

.Ltw_join_213_1:
	s_waitcnt lgkmcnt(0)
	s_barrier
	s_setprio 1
	s_waitcnt lgkmcnt(0)
	v_mfma_f32_16x16x32_bf16 v[62:65], v[144:147], v[176:179], v[62:65]
	v_mfma_f32_16x16x32_bf16 v[58:61], v[152:155], v[176:179], v[58:61]
	v_mfma_f32_16x16x32_bf16 v[54:57], v[144:147], v[190:193], v[54:57]
	v_mfma_f32_16x16x32_bf16 v[50:53], v[152:155], v[190:193], v[50:53]
	v_mfma_f32_16x16x32_bf16 v[38:41], v[144:147], v[216:219], v[38:41]
	v_mfma_f32_16x16x32_bf16 v[34:37], v[152:155], v[216:219], v[34:37]
	v_mfma_f32_16x16x32_bf16 v[22:25], v[144:147], v[224:227], v[22:25]
	v_mfma_f32_16x16x32_bf16 v[18:21], v[152:155], v[224:227], v[18:21]
	v_mfma_f32_16x16x32_bf16 v[62:65], v[148:151], v[186:189], v[62:65]
	v_mfma_f32_16x16x32_bf16 v[58:61], v[156:159], v[186:189], v[58:61]
	v_mfma_f32_16x16x32_bf16 v[54:57], v[148:151], v[212:215], v[54:57]
	v_mfma_f32_16x16x32_bf16 v[50:53], v[156:159], v[212:215], v[50:53]
	v_mfma_f32_16x16x32_bf16 v[38:41], v[148:151], v[220:223], v[38:41]
	v_mfma_f32_16x16x32_bf16 v[34:37], v[156:159], v[220:223], v[34:37]
	v_mfma_f32_16x16x32_bf16 v[22:25], v[148:151], v[228:231], v[22:25]
	v_mfma_f32_16x16x32_bf16 v[18:21], v[156:159], v[228:231], v[18:21]
	s_setprio 0
	s_setprio 1
	v_mfma_f32_16x16x32_bf16 v[46:49], v[160:163], v[176:179], v[46:49]
	v_mfma_f32_16x16x32_bf16 v[42:45], v[168:171], v[176:179], v[42:45]
	v_mfma_f32_16x16x32_bf16 v[30:33], v[160:163], v[190:193], v[30:33]
	v_mfma_f32_16x16x32_bf16 v[26:29], v[168:171], v[190:193], v[26:29]
	v_mfma_f32_16x16x32_bf16 v[14:17], v[160:163], v[216:219], v[14:17]
	v_mfma_f32_16x16x32_bf16 v[10:13], v[168:171], v[216:219], v[10:13]
	v_mfma_f32_16x16x32_bf16 v[6:9], v[160:163], v[224:227], v[6:9]
	v_mfma_f32_16x16x32_bf16 v[2:5], v[168:171], v[224:227], v[2:5]
	v_mfma_f32_16x16x32_bf16 v[46:49], v[164:167], v[186:189], v[46:49]
	v_mfma_f32_16x16x32_bf16 v[42:45], v[172:175], v[186:189], v[42:45]
	v_mfma_f32_16x16x32_bf16 v[30:33], v[164:167], v[212:215], v[30:33]
	v_mfma_f32_16x16x32_bf16 v[26:29], v[172:175], v[212:215], v[26:29]
	v_mfma_f32_16x16x32_bf16 v[14:17], v[164:167], v[220:223], v[14:17]
	v_mfma_f32_16x16x32_bf16 v[10:13], v[172:175], v[220:223], v[10:13]
	v_mfma_f32_16x16x32_bf16 v[6:9], v[164:167], v[228:231], v[6:9]
	v_mfma_f32_16x16x32_bf16 v[2:5], v[172:175], v[228:231], v[2:5]
	s_setprio 0
	s_barrier
	s_add_i32 s48, 0, 0x18000
	s_add_i32 s49, 0, 0x1c000
	v_add_u32_e32 v156, s48, v141
	v_add_u32_e32 v172, s49, v141
	ds_read_b128 v[144:147], v156
	ds_read_b128 v[148:151], v156 offset:1024
	ds_read_b128 v[152:155], v156 offset:2048
	ds_read_b128 v[156:159], v156 offset:3072
	ds_read_b128 v[160:163], v172
	ds_read_b128 v[164:167], v172 offset:1024
	ds_read_b128 v[168:171], v172 offset:2048
	ds_read_b128 v[172:175], v172 offset:3072
	s_add_u32 s22, s22, 0x40000
	s_addc_u32 s23, s23, 0
	s_mov_b32 m0, s31
	v_lshl_add_u64 v[236:237], s[22:23], 0, v[134:135]
	ds_read_b128 v[176:179], v143 offset:32768
	ds_read_b128 v[186:189], v143 offset:33792
	ds_read_b128 v[190:193], v143 offset:34816
	ds_read_b128 v[212:215], v143 offset:35840
	ds_read_b128 v[216:219], v143 offset:36864
	ds_read_b128 v[220:223], v143 offset:37888
	ds_read_b128 v[224:227], v143 offset:38912
	ds_read_b128 v[228:231], v143 offset:39936
	global_load_lds_dwordx4 v[236:237], off
	v_lshl_add_u64 v[236:237], s[22:23], 0, v[132:133]
	s_mov_b32 m0, s34
	s_nop 0
	global_load_lds_dwordx4 v[236:237], off
	s_waitcnt vmcnt(8)
	s_waitcnt lgkmcnt(0)
	s_barrier
	s_setprio 1
	s_waitcnt lgkmcnt(0)
	v_mfma_f32_16x16x32_bf16 v[126:129], v[144:147], v[176:179], v[126:129]
	v_mfma_f32_16x16x32_bf16 v[122:125], v[152:155], v[176:179], v[122:125]
	v_mfma_f32_16x16x32_bf16 v[118:121], v[144:147], v[190:193], v[118:121]
	v_mfma_f32_16x16x32_bf16 v[114:117], v[152:155], v[190:193], v[114:117]
	v_mfma_f32_16x16x32_bf16 v[102:105], v[144:147], v[216:219], v[102:105]
	v_mfma_f32_16x16x32_bf16 v[98:101], v[152:155], v[216:219], v[98:101]
	v_mfma_f32_16x16x32_bf16 v[86:89], v[144:147], v[224:227], v[86:89]
	v_mfma_f32_16x16x32_bf16 v[82:85], v[152:155], v[224:227], v[82:85]
	v_mfma_f32_16x16x32_bf16 v[126:129], v[148:151], v[186:189], v[126:129]
	v_mfma_f32_16x16x32_bf16 v[122:125], v[156:159], v[186:189], v[122:125]
	v_mfma_f32_16x16x32_bf16 v[118:121], v[148:151], v[212:215], v[118:121]
	v_mfma_f32_16x16x32_bf16 v[114:117], v[156:159], v[212:215], v[114:117]
	v_mfma_f32_16x16x32_bf16 v[102:105], v[148:151], v[220:223], v[102:105]
	v_mfma_f32_16x16x32_bf16 v[98:101], v[156:159], v[220:223], v[98:101]
	v_mfma_f32_16x16x32_bf16 v[86:89], v[148:151], v[228:231], v[86:89]
	v_mfma_f32_16x16x32_bf16 v[82:85], v[156:159], v[228:231], v[82:85]
	s_setprio 0
	s_setprio 1
	v_mfma_f32_16x16x32_bf16 v[110:113], v[160:163], v[176:179], v[110:113]
	v_mfma_f32_16x16x32_bf16 v[106:109], v[168:171], v[176:179], v[106:109]
	v_mfma_f32_16x16x32_bf16 v[94:97], v[160:163], v[190:193], v[94:97]
	v_mfma_f32_16x16x32_bf16 v[90:93], v[168:171], v[190:193], v[90:93]
	v_mfma_f32_16x16x32_bf16 v[78:81], v[160:163], v[216:219], v[78:81]
	v_mfma_f32_16x16x32_bf16 v[74:77], v[168:171], v[216:219], v[74:77]
	v_mfma_f32_16x16x32_bf16 v[70:73], v[160:163], v[224:227], v[70:73]
	v_mfma_f32_16x16x32_bf16 v[66:69], v[168:171], v[224:227], v[66:69]
	v_mfma_f32_16x16x32_bf16 v[110:113], v[164:167], v[186:189], v[110:113]
	v_mfma_f32_16x16x32_bf16 v[106:109], v[172:175], v[186:189], v[106:109]
	v_mfma_f32_16x16x32_bf16 v[94:97], v[164:167], v[212:215], v[94:97]
	v_mfma_f32_16x16x32_bf16 v[90:93], v[172:175], v[212:215], v[90:93]
	v_mfma_f32_16x16x32_bf16 v[78:81], v[164:167], v[220:223], v[78:81]
	v_mfma_f32_16x16x32_bf16 v[74:77], v[172:175], v[220:223], v[74:77]
	v_mfma_f32_16x16x32_bf16 v[70:73], v[164:167], v[228:231], v[70:73]
	v_mfma_f32_16x16x32_bf16 v[66:69], v[172:175], v[228:231], v[66:69]
	s_setprio 0
	s_barrier
	s_add_i32 s22, s48, s28
	v_lshl_add_u64 v[180:181], v[180:181], 0, s[16:17]
	s_mov_b32 m0, s22
	ds_read_b128 v[176:179], v143 offset:49152
	ds_read_b128 v[186:189], v143 offset:50176
	ds_read_b128 v[190:193], v143 offset:51200
	ds_read_b128 v[212:215], v143 offset:52224
	ds_read_b128 v[216:219], v143 offset:53248
	ds_read_b128 v[220:223], v143 offset:54272
	ds_read_b128 v[224:227], v143 offset:55296
	ds_read_b128 v[228:231], v143 offset:56320
	global_load_lds_dwordx4 v[180:181], off
	s_add_i32 m0, s22, 0x2000
	s_add_u32 s20, s20, 0x40080
	v_lshl_add_u64 v[180:181], v[194:195], 0, s[16:17]
	s_addc_u32 s21, s21, 0
	s_add_i32 s22, s49, s28
	global_load_lds_dwordx4 v[180:181], off
	v_lshl_add_u64 v[180:181], s[20:21], 0, v[0:1]
	s_mov_b32 m0, s22
	s_nop 0
	global_load_lds_dwordx4 v[180:181], off
	v_lshl_add_u64 v[180:181], s[20:21], 0, v[130:131]
	s_add_i32 m0, s22, 0x2000
	s_nop 0
	global_load_lds_dwordx4 v[180:181], off
	v_lshl_add_u64 v[180:181], v[232:233], 0, s[16:17]
	s_mov_b32 m0, s35
	s_nop 0
	global_load_lds_dwordx4 v[180:181], off
	v_lshl_add_u64 v[180:181], v[234:235], 0, s[16:17]
	s_mov_b32 m0, s36
	s_nop 0
	global_load_lds_dwordx4 v[180:181], off
	s_waitcnt vmcnt(8)
	s_waitcnt lgkmcnt(0)
	s_barrier
	s_setprio 1
	s_waitcnt lgkmcnt(0)
	v_mfma_f32_16x16x32_bf16 v[62:65], v[144:147], v[176:179], v[62:65]
	v_mfma_f32_16x16x32_bf16 v[58:61], v[152:155], v[176:179], v[58:61]
	v_mfma_f32_16x16x32_bf16 v[54:57], v[144:147], v[190:193], v[54:57]
	v_mfma_f32_16x16x32_bf16 v[50:53], v[152:155], v[190:193], v[50:53]
	v_mfma_f32_16x16x32_bf16 v[38:41], v[144:147], v[216:219], v[38:41]
	v_mfma_f32_16x16x32_bf16 v[34:37], v[152:155], v[216:219], v[34:37]
	v_mfma_f32_16x16x32_bf16 v[22:25], v[144:147], v[224:227], v[22:25]
	v_mfma_f32_16x16x32_bf16 v[18:21], v[152:155], v[224:227], v[18:21]
	v_mfma_f32_16x16x32_bf16 v[62:65], v[148:151], v[186:189], v[62:65]
	v_mfma_f32_16x16x32_bf16 v[58:61], v[156:159], v[186:189], v[58:61]
	v_mfma_f32_16x16x32_bf16 v[54:57], v[148:151], v[212:215], v[54:57]
	v_mfma_f32_16x16x32_bf16 v[50:53], v[156:159], v[212:215], v[50:53]
	v_mfma_f32_16x16x32_bf16 v[38:41], v[148:151], v[220:223], v[38:41]
	v_mfma_f32_16x16x32_bf16 v[34:37], v[156:159], v[220:223], v[34:37]
	v_mfma_f32_16x16x32_bf16 v[22:25], v[148:151], v[228:231], v[22:25]
	v_mfma_f32_16x16x32_bf16 v[18:21], v[156:159], v[228:231], v[18:21]
	s_setprio 0
	s_setprio 1
	v_mfma_f32_16x16x32_bf16 v[46:49], v[160:163], v[176:179], v[46:49]
	v_mfma_f32_16x16x32_bf16 v[42:45], v[168:171], v[176:179], v[42:45]
	v_mfma_f32_16x16x32_bf16 v[30:33], v[160:163], v[190:193], v[30:33]
	v_mfma_f32_16x16x32_bf16 v[26:29], v[168:171], v[190:193], v[26:29]
	v_mfma_f32_16x16x32_bf16 v[14:17], v[160:163], v[216:219], v[14:17]
	v_mfma_f32_16x16x32_bf16 v[10:13], v[168:171], v[216:219], v[10:13]
	v_mfma_f32_16x16x32_bf16 v[6:9], v[160:163], v[224:227], v[6:9]
	v_mfma_f32_16x16x32_bf16 v[2:5], v[168:171], v[224:227], v[2:5]
	v_mfma_f32_16x16x32_bf16 v[46:49], v[164:167], v[186:189], v[46:49]
	v_mfma_f32_16x16x32_bf16 v[42:45], v[172:175], v[186:189], v[42:45]
	v_mfma_f32_16x16x32_bf16 v[30:33], v[164:167], v[212:215], v[30:33]
	v_mfma_f32_16x16x32_bf16 v[26:29], v[172:175], v[212:215], v[26:29]
	v_mfma_f32_16x16x32_bf16 v[14:17], v[164:167], v[220:223], v[14:17]
	v_mfma_f32_16x16x32_bf16 v[10:13], v[172:175], v[220:223], v[10:13]
	v_mfma_f32_16x16x32_bf16 v[6:9], v[164:167], v[228:231], v[6:9]
	v_mfma_f32_16x16x32_bf16 v[2:5], v[172:175], v[228:231], v[2:5]
	s_setprio 0
	s_barrier
	s_add_i32 s46, s46, 2
	s_add_u32 s18, s18, 0x100
	s_addc_u32 s19, s19, 0
	s_add_u32 s44, s44, 0x100
	s_addc_u32 s45, s45, 0
	s_cmp_gt_u32 s46, 13
	s_cbranch_scc0 .LBB0_213
	s_and_b64 vcc, exec, s[6:7]
	s_cbranch_vccz .LBB0_216
	s_barrier

.LBB0_684:
	s_add_u32 s22, s20, 0xfffc0080
	s_addc_u32 s23, s21, -1
	s_add_i32 s53, 0, 0x10000
	s_cmp_eq_u32 s52, 12
	s_cselect_b32 s25, s11, s23
	s_cselect_b32 s24, s48, s22
	s_cselect_b32 s23, s9, s51
	s_cselect_b32 s22, s49, s50
	s_add_i32 s56, 0, 0x14000
	v_add_u32_e32 v156, s53, v145
	v_add_u32_e32 v172, s56, v145
	ds_read_b128 v[140:143], v156
	ds_read_b128 v[148:151], v156 offset:1024
	ds_read_b128 v[152:155], v156 offset:2048
	ds_read_b128 v[156:159], v156 offset:3072
	ds_read_b128 v[160:163], v172
	ds_read_b128 v[164:167], v172 offset:1024
	ds_read_b128 v[168:171], v172 offset:2048
	ds_read_b128 v[172:175], v172 offset:3072
	v_lshl_add_u64 v[180:181], s[20:21], 0, v[136:137]
	s_add_i32 m0, s35, 0xc000
	ds_read_b128 v[176:179], v147
	ds_read_b128 v[186:189], v147 offset:1024
	ds_read_b128 v[190:193], v147 offset:2048
	ds_read_b128 v[212:215], v147 offset:3072
	ds_read_b128 v[216:219], v147 offset:4096
	ds_read_b128 v[220:223], v147 offset:5120
	ds_read_b128 v[224:227], v147 offset:6144
	ds_read_b128 v[228:231], v147 offset:7168
	global_load_lds_dwordx4 v[180:181], off
	v_lshl_add_u64 v[180:181], s[20:21], 0, v[138:139]
	s_add_i32 m0, s35, 0xe000
	s_nop 0
	global_load_lds_dwordx4 v[180:181], off
	s_cmp_eq_u32 s52, -2
	s_cselect_b32 s98, s45, 0
	s_cmp_gt_u32 s98, 1
	s_cbranch_scc1 .Ltw_relax_684_0
	s_waitcnt vmcnt(8)
	s_branch .Ltw_join_684_0

.Ltw_join_684_0:
	s_waitcnt lgkmcnt(0)
	s_barrier
	s_setprio 1
	s_waitcnt lgkmcnt(0)
	v_mfma_f32_16x16x32_bf16 v[126:129], v[140:143], v[176:179], v[126:129]
	v_mfma_f32_16x16x32_bf16 v[122:125], v[152:155], v[176:179], v[122:125]
	v_mfma_f32_16x16x32_bf16 v[110:113], v[140:143], v[190:193], v[110:113]
	v_mfma_f32_16x16x32_bf16 v[106:109], v[152:155], v[190:193], v[106:109]
	v_mfma_f32_16x16x32_bf16 v[94:97], v[140:143], v[216:219], v[94:97]
	v_mfma_f32_16x16x32_bf16 v[90:93], v[152:155], v[216:219], v[90:93]
	v_mfma_f32_16x16x32_bf16 v[78:81], v[140:143], v[224:227], v[78:81]
	v_mfma_f32_16x16x32_bf16 v[74:77], v[152:155], v[224:227], v[74:77]
	v_mfma_f32_16x16x32_bf16 v[126:129], v[148:151], v[186:189], v[126:129]
	v_mfma_f32_16x16x32_bf16 v[122:125], v[156:159], v[186:189], v[122:125]
	v_mfma_f32_16x16x32_bf16 v[110:113], v[148:151], v[212:215], v[110:113]
	v_mfma_f32_16x16x32_bf16 v[106:109], v[156:159], v[212:215], v[106:109]
	v_mfma_f32_16x16x32_bf16 v[94:97], v[148:151], v[220:223], v[94:97]
	v_mfma_f32_16x16x32_bf16 v[90:93], v[156:159], v[220:223], v[90:93]
	v_mfma_f32_16x16x32_bf16 v[78:81], v[148:151], v[228:231], v[78:81]
	v_mfma_f32_16x16x32_bf16 v[74:77], v[156:159], v[228:231], v[74:77]
	s_setprio 0
	s_setprio 1
	v_mfma_f32_16x16x32_bf16 v[118:121], v[160:163], v[176:179], v[118:121]
	v_mfma_f32_16x16x32_bf16 v[114:117], v[168:171], v[176:179], v[114:117]
	v_mfma_f32_16x16x32_bf16 v[102:105], v[160:163], v[190:193], v[102:105]
	v_mfma_f32_16x16x32_bf16 v[98:101], v[168:171], v[190:193], v[98:101]
	v_mfma_f32_16x16x32_bf16 v[86:89], v[160:163], v[216:219], v[86:89]
	v_mfma_f32_16x16x32_bf16 v[82:85], v[168:171], v[216:219], v[82:85]
	v_mfma_f32_16x16x32_bf16 v[70:73], v[160:163], v[224:227], v[70:73]
	v_mfma_f32_16x16x32_bf16 v[66:69], v[168:171], v[224:227], v[66:69]
	v_mfma_f32_16x16x32_bf16 v[118:121], v[164:167], v[186:189], v[118:121]
	v_mfma_f32_16x16x32_bf16 v[114:117], v[172:175], v[186:189], v[114:117]
	v_mfma_f32_16x16x32_bf16 v[102:105], v[164:167], v[212:215], v[102:105]
	v_mfma_f32_16x16x32_bf16 v[98:101], v[172:175], v[212:215], v[98:101]
	v_mfma_f32_16x16x32_bf16 v[86:89], v[164:167], v[220:223], v[86:89]
	v_mfma_f32_16x16x32_bf16 v[82:85], v[172:175], v[220:223], v[82:85]
	v_mfma_f32_16x16x32_bf16 v[70:73], v[164:167], v[228:231], v[70:73]
	v_mfma_f32_16x16x32_bf16 v[66:69], v[172:175], v[228:231], v[66:69]
	s_setprio 0
	s_barrier
	s_add_i32 s53, s53, s31
	v_lshl_add_u64 v[180:181], s[22:23], 0, v[0:1]
	s_mov_b32 m0, s53
	ds_read_b128 v[176:179], v147 offset:16384
	ds_read_b128 v[186:189], v147 offset:17408
	ds_read_b128 v[190:193], v147 offset:18432
	ds_read_b128 v[212:215], v147 offset:19456
	ds_read_b128 v[216:219], v147 offset:20480
	ds_read_b128 v[220:223], v147 offset:21504
	ds_read_b128 v[224:227], v147 offset:22528
	ds_read_b128 v[228:231], v147 offset:23552
	global_load_lds_dwordx4 v[180:181], off
	s_add_i32 m0, s53, 0x2000
	s_add_u32 s54, s22, 0x40000
	v_lshl_add_u64 v[194:195], s[22:23], 0, v[134:135]
	s_addc_u32 s55, s23, 0
	s_add_i32 s53, s56, s31
	global_load_lds_dwordx4 v[194:195], off
	v_lshl_add_u64 v[232:233], s[54:55], 0, v[0:1]
	s_mov_b32 m0, s53
	v_lshl_add_u64 v[234:235], s[24:25], 0, v[132:133]
	global_load_lds_dwordx4 v[232:233], off
	v_lshl_add_u64 v[232:233], s[54:55], 0, v[134:135]
	s_add_i32 m0, s53, 0x2000
	s_nop 0
	global_load_lds_dwordx4 v[232:233], off
	v_lshl_add_u64 v[232:233], s[24:25], 0, v[130:131]
	s_mov_b32 m0, s35
	s_nop 0
	global_load_lds_dwordx4 v[232:233], off
	s_mov_b32 m0, s36
	s_nop 0
	global_load_lds_dwordx4 v[234:235], off
	s_cmp_eq_u32 s52, -2
	s_cselect_b32 s98, s45, 0
	s_cmp_gt_u32 s98, 1
	s_cbranch_scc1 .Ltw_relax_684_1
	s_waitcnt vmcnt(8)
	s_branch .Ltw_join_684_1

.Ltw_join_684_1:
	s_waitcnt lgkmcnt(0)
	s_barrier
	s_setprio 1
	s_waitcnt lgkmcnt(0)
	v_mfma_f32_16x16x32_bf16 v[62:65], v[140:143], v[176:179], v[62:65]
	v_mfma_f32_16x16x32_bf16 v[58:61], v[152:155], v[176:179], v[58:61]
	v_mfma_f32_16x16x32_bf16 v[46:49], v[140:143], v[190:193], v[46:49]
	v_mfma_f32_16x16x32_bf16 v[42:45], v[152:155], v[190:193], v[42:45]
	v_mfma_f32_16x16x32_bf16 v[30:33], v[140:143], v[216:219], v[30:33]
	v_mfma_f32_16x16x32_bf16 v[26:29], v[152:155], v[216:219], v[26:29]
	v_mfma_f32_16x16x32_bf16 v[14:17], v[140:143], v[224:227], v[14:17]
	v_mfma_f32_16x16x32_bf16 v[10:13], v[152:155], v[224:227], v[10:13]
	v_mfma_f32_16x16x32_bf16 v[62:65], v[148:151], v[186:189], v[62:65]
	v_mfma_f32_16x16x32_bf16 v[58:61], v[156:159], v[186:189], v[58:61]
	v_mfma_f32_16x16x32_bf16 v[46:49], v[148:151], v[212:215], v[46:49]
	v_mfma_f32_16x16x32_bf16 v[42:45], v[156:159], v[212:215], v[42:45]
	v_mfma_f32_16x16x32_bf16 v[30:33], v[148:151], v[220:223], v[30:33]
	v_mfma_f32_16x16x32_bf16 v[26:29], v[156:159], v[220:223], v[26:29]
	v_mfma_f32_16x16x32_bf16 v[14:17], v[148:151], v[228:231], v[14:17]
	v_mfma_f32_16x16x32_bf16 v[10:13], v[156:159], v[228:231], v[10:13]
	s_setprio 0
	s_setprio 1
	v_mfma_f32_16x16x32_bf16 v[54:57], v[160:163], v[176:179], v[54:57]
	v_mfma_f32_16x16x32_bf16 v[50:53], v[168:171], v[176:179], v[50:53]
	v_mfma_f32_16x16x32_bf16 v[38:41], v[160:163], v[190:193], v[38:41]
	v_mfma_f32_16x16x32_bf16 v[34:37], v[168:171], v[190:193], v[34:37]
	v_mfma_f32_16x16x32_bf16 v[22:25], v[160:163], v[216:219], v[22:25]
	v_mfma_f32_16x16x32_bf16 v[18:21], v[168:171], v[216:219], v[18:21]
	v_mfma_f32_16x16x32_bf16 v[6:9], v[160:163], v[224:227], v[6:9]
	v_mfma_f32_16x16x32_bf16 v[2:5], v[168:171], v[224:227], v[2:5]
	v_mfma_f32_16x16x32_bf16 v[54:57], v[164:167], v[186:189], v[54:57]
	v_mfma_f32_16x16x32_bf16 v[50:53], v[172:175], v[186:189], v[50:53]
	v_mfma_f32_16x16x32_bf16 v[38:41], v[164:167], v[212:215], v[38:41]
	v_mfma_f32_16x16x32_bf16 v[34:37], v[172:175], v[212:215], v[34:37]
	v_mfma_f32_16x16x32_bf16 v[22:25], v[164:167], v[220:223], v[22:25]
	v_mfma_f32_16x16x32_bf16 v[18:21], v[172:175], v[220:223], v[18:21]
	v_mfma_f32_16x16x32_bf16 v[6:9], v[164:167], v[228:231], v[6:9]
	v_mfma_f32_16x16x32_bf16 v[2:5], v[172:175], v[228:231], v[2:5]
	s_setprio 0
	s_barrier
	s_add_i32 s53, 0, 0x18000
	s_add_i32 s54, 0, 0x1c000
	v_add_u32_e32 v156, s53, v145
	v_add_u32_e32 v172, s54, v145
	ds_read_b128 v[140:143], v156
	ds_read_b128 v[148:151], v156 offset:1024
	ds_read_b128 v[152:155], v156 offset:2048
	ds_read_b128 v[156:159], v156 offset:3072
	ds_read_b128 v[160:163], v172
	ds_read_b128 v[164:167], v172 offset:1024
	ds_read_b128 v[168:171], v172 offset:2048
	ds_read_b128 v[172:175], v172 offset:3072
	s_add_u32 s24, s24, 0x40000
	s_addc_u32 s25, s25, 0
	s_mov_b32 m0, s37
	v_lshl_add_u64 v[236:237], s[24:25], 0, v[130:131]
	ds_read_b128 v[176:179], v147 offset:32768
	ds_read_b128 v[186:189], v147 offset:33792
	ds_read_b128 v[190:193], v147 offset:34816
	ds_read_b128 v[212:215], v147 offset:35840
	ds_read_b128 v[216:219], v147 offset:36864
	ds_read_b128 v[220:223], v147 offset:37888
	ds_read_b128 v[224:227], v147 offset:38912
	ds_read_b128 v[228:231], v147 offset:39936
	global_load_lds_dwordx4 v[236:237], off
	v_lshl_add_u64 v[236:237], s[24:25], 0, v[132:133]
	s_mov_b32 m0, s42
	s_nop 0
	global_load_lds_dwordx4 v[236:237], off
	s_waitcnt vmcnt(8)
	s_waitcnt lgkmcnt(0)
	s_barrier
	s_setprio 1
	s_waitcnt lgkmcnt(0)
	v_mfma_f32_16x16x32_bf16 v[126:129], v[140:143], v[176:179], v[126:129]
	v_mfma_f32_16x16x32_bf16 v[122:125], v[152:155], v[176:179], v[122:125]
	v_mfma_f32_16x16x32_bf16 v[110:113], v[140:143], v[190:193], v[110:113]
	v_mfma_f32_16x16x32_bf16 v[106:109], v[152:155], v[190:193], v[106:109]
	v_mfma_f32_16x16x32_bf16 v[94:97], v[140:143], v[216:219], v[94:97]
	v_mfma_f32_16x16x32_bf16 v[90:93], v[152:155], v[216:219], v[90:93]
	v_mfma_f32_16x16x32_bf16 v[78:81], v[140:143], v[224:227], v[78:81]
	v_mfma_f32_16x16x32_bf16 v[74:77], v[152:155], v[224:227], v[74:77]
	v_mfma_f32_16x16x32_bf16 v[126:129], v[148:151], v[186:189], v[126:129]
	v_mfma_f32_16x16x32_bf16 v[122:125], v[156:159], v[186:189], v[122:125]
	v_mfma_f32_16x16x32_bf16 v[110:113], v[148:151], v[212:215], v[110:113]
	v_mfma_f32_16x16x32_bf16 v[106:109], v[156:159], v[212:215], v[106:109]
	v_mfma_f32_16x16x32_bf16 v[94:97], v[148:151], v[220:223], v[94:97]
	v_mfma_f32_16x16x32_bf16 v[90:93], v[156:159], v[220:223], v[90:93]
	v_mfma_f32_16x16x32_bf16 v[78:81], v[148:151], v[228:231], v[78:81]
	v_mfma_f32_16x16x32_bf16 v[74:77], v[156:159], v[228:231], v[74:77]
	s_setprio 0
	s_setprio 1
	v_mfma_f32_16x16x32_bf16 v[118:121], v[160:163], v[176:179], v[118:121]
	v_mfma_f32_16x16x32_bf16 v[114:117], v[168:171], v[176:179], v[114:117]
	v_mfma_f32_16x16x32_bf16 v[102:105], v[160:163], v[190:193], v[102:105]
	v_mfma_f32_16x16x32_bf16 v[98:101], v[168:171], v[190:193], v[98:101]
	v_mfma_f32_16x16x32_bf16 v[86:89], v[160:163], v[216:219], v[86:89]
	v_mfma_f32_16x16x32_bf16 v[82:85], v[168:171], v[216:219], v[82:85]
	v_mfma_f32_16x16x32_bf16 v[70:73], v[160:163], v[224:227], v[70:73]
	v_mfma_f32_16x16x32_bf16 v[66:69], v[168:171], v[224:227], v[66:69]
	v_mfma_f32_16x16x32_bf16 v[118:121], v[164:167], v[186:189], v[118:121]
	v_mfma_f32_16x16x32_bf16 v[114:117], v[172:175], v[186:189], v[114:117]
	v_mfma_f32_16x16x32_bf16 v[102:105], v[164:167], v[212:215], v[102:105]
	v_mfma_f32_16x16x32_bf16 v[98:101], v[172:175], v[212:215], v[98:101]
	v_mfma_f32_16x16x32_bf16 v[86:89], v[164:167], v[220:223], v[86:89]
	v_mfma_f32_16x16x32_bf16 v[82:85], v[172:175], v[220:223], v[82:85]
	v_mfma_f32_16x16x32_bf16 v[70:73], v[164:167], v[228:231], v[70:73]
	v_mfma_f32_16x16x32_bf16 v[66:69], v[172:175], v[228:231], v[66:69]
	s_setprio 0
	s_barrier
	s_add_i32 s24, s53, s31
	v_lshl_add_u64 v[180:181], v[180:181], 0, s[16:17]
	s_mov_b32 m0, s24
	ds_read_b128 v[176:179], v147 offset:49152
	ds_read_b128 v[186:189], v147 offset:50176
	ds_read_b128 v[190:193], v147 offset:51200
	ds_read_b128 v[212:215], v147 offset:52224
	ds_read_b128 v[216:219], v147 offset:53248
	ds_read_b128 v[220:223], v147 offset:54272
	ds_read_b128 v[224:227], v147 offset:55296
	ds_read_b128 v[228:231], v147 offset:56320
	global_load_lds_dwordx4 v[180:181], off
	s_add_i32 m0, s24, 0x2000
	s_add_u32 s22, s22, 0x40080
	v_lshl_add_u64 v[180:181], v[194:195], 0, s[16:17]
	s_addc_u32 s23, s23, 0
	s_add_i32 s24, s54, s31
	global_load_lds_dwordx4 v[180:181], off
	v_lshl_add_u64 v[180:181], s[22:23], 0, v[0:1]
	s_mov_b32 m0, s24
	s_nop 0
	global_load_lds_dwordx4 v[180:181], off
	v_lshl_add_u64 v[180:181], s[22:23], 0, v[134:135]
	s_add_i32 m0, s24, 0x2000
	s_nop 0
	global_load_lds_dwordx4 v[180:181], off
	v_lshl_add_u64 v[180:181], v[232:233], 0, s[16:17]
	s_mov_b32 m0, s43
	s_nop 0
	global_load_lds_dwordx4 v[180:181], off
	v_lshl_add_u64 v[180:181], v[234:235], 0, s[16:17]
	s_mov_b32 m0, s44
	s_nop 0
	global_load_lds_dwordx4 v[180:181], off
	s_waitcnt vmcnt(8)
	s_waitcnt lgkmcnt(0)
	s_barrier
	s_setprio 1
	s_waitcnt lgkmcnt(0)
	v_mfma_f32_16x16x32_bf16 v[62:65], v[140:143], v[176:179], v[62:65]
	v_mfma_f32_16x16x32_bf16 v[58:61], v[152:155], v[176:179], v[58:61]
	v_mfma_f32_16x16x32_bf16 v[46:49], v[140:143], v[190:193], v[46:49]
	v_mfma_f32_16x16x32_bf16 v[42:45], v[152:155], v[190:193], v[42:45]
	v_mfma_f32_16x16x32_bf16 v[30:33], v[140:143], v[216:219], v[30:33]
	v_mfma_f32_16x16x32_bf16 v[26:29], v[152:155], v[216:219], v[26:29]
	v_mfma_f32_16x16x32_bf16 v[14:17], v[140:143], v[224:227], v[14:17]
	v_mfma_f32_16x16x32_bf16 v[10:13], v[152:155], v[224:227], v[10:13]
	v_mfma_f32_16x16x32_bf16 v[62:65], v[148:151], v[186:189], v[62:65]
	v_mfma_f32_16x16x32_bf16 v[58:61], v[156:159], v[186:189], v[58:61]
	v_mfma_f32_16x16x32_bf16 v[46:49], v[148:151], v[212:215], v[46:49]
	v_mfma_f32_16x16x32_bf16 v[42:45], v[156:159], v[212:215], v[42:45]
	v_mfma_f32_16x16x32_bf16 v[30:33], v[148:151], v[220:223], v[30:33]
	v_mfma_f32_16x16x32_bf16 v[26:29], v[156:159], v[220:223], v[26:29]
	v_mfma_f32_16x16x32_bf16 v[14:17], v[148:151], v[228:231], v[14:17]
	v_mfma_f32_16x16x32_bf16 v[10:13], v[156:159], v[228:231], v[10:13]
	s_setprio 0
	s_setprio 1
	v_mfma_f32_16x16x32_bf16 v[54:57], v[160:163], v[176:179], v[54:57]
	v_mfma_f32_16x16x32_bf16 v[50:53], v[168:171], v[176:179], v[50:53]
	v_mfma_f32_16x16x32_bf16 v[38:41], v[160:163], v[190:193], v[38:41]
	v_mfma_f32_16x16x32_bf16 v[34:37], v[168:171], v[190:193], v[34:37]
	v_mfma_f32_16x16x32_bf16 v[22:25], v[160:163], v[216:219], v[22:25]
	v_mfma_f32_16x16x32_bf16 v[18:21], v[168:171], v[216:219], v[18:21]
	v_mfma_f32_16x16x32_bf16 v[6:9], v[160:163], v[224:227], v[6:9]
	v_mfma_f32_16x16x32_bf16 v[2:5], v[168:171], v[224:227], v[2:5]
	v_mfma_f32_16x16x32_bf16 v[54:57], v[164:167], v[186:189], v[54:57]
	v_mfma_f32_16x16x32_bf16 v[50:53], v[172:175], v[186:189], v[50:53]
	v_mfma_f32_16x16x32_bf16 v[38:41], v[164:167], v[212:215], v[38:41]
	v_mfma_f32_16x16x32_bf16 v[34:37], v[172:175], v[212:215], v[34:37]
	v_mfma_f32_16x16x32_bf16 v[22:25], v[164:167], v[220:223], v[22:25]
	v_mfma_f32_16x16x32_bf16 v[18:21], v[172:175], v[220:223], v[18:21]
	v_mfma_f32_16x16x32_bf16 v[6:9], v[164:167], v[228:231], v[6:9]
	v_mfma_f32_16x16x32_bf16 v[2:5], v[172:175], v[228:231], v[2:5]
	s_setprio 0
	s_barrier
	s_add_i32 s52, s52, 2
	s_add_u32 s20, s20, 0x100
	s_addc_u32 s21, s21, 0
	s_add_u32 s50, s50, 0x100
	s_addc_u32 s51, s51, 0
	s_cmp_gt_u32 s52, 13
	s_cbranch_scc0 .LBB0_684
	s_and_b64 vcc, exec, s[6:7]
	s_cbranch_vccz .LBB0_687
	s_barrier

.LBB0_1027:
	s_add_u32 s26, s24, 0xfffc0080
	s_addc_u32 s27, s25, -1
	s_add_i32 s63, 0, 0x10000
	s_cmp_eq_u32 s62, 12
	s_cselect_b32 s29, s13, s27
	s_cselect_b32 s28, s15, s26
	s_cselect_b32 s27, s11, s61
	s_cselect_b32 s26, s59, s60
	s_add_i32 s67, 0, 0x14000
	v_add_u32_e32 v156, s63, v145
	v_add_u32_e32 v172, s67, v145
	ds_read_b128 v[140:143], v156
	ds_read_b128 v[148:151], v156 offset:1024
	ds_read_b128 v[152:155], v156 offset:2048
	ds_read_b128 v[156:159], v156 offset:3072
	ds_read_b128 v[160:163], v172
	ds_read_b128 v[164:167], v172 offset:1024
	ds_read_b128 v[168:171], v172 offset:2048
	ds_read_b128 v[172:175], v172 offset:3072
	v_lshl_add_u64 v[180:181], s[24:25], 0, v[136:137]
	s_add_i32 m0, s19, 0xc000
	ds_read_b128 v[176:179], v147
	ds_read_b128 v[186:189], v147 offset:1024
	ds_read_b128 v[190:193], v147 offset:2048
	ds_read_b128 v[212:215], v147 offset:3072
	ds_read_b128 v[216:219], v147 offset:4096
	ds_read_b128 v[220:223], v147 offset:5120
	ds_read_b128 v[224:227], v147 offset:6144
	ds_read_b128 v[228:231], v147 offset:7168
	global_load_lds_dwordx4 v[180:181], off
	v_lshl_add_u64 v[180:181], s[24:25], 0, v[138:139]
	s_add_i32 m0, s19, 0xe000
	s_nop 0
	global_load_lds_dwordx4 v[180:181], off
	s_cmp_eq_u32 s62, -2
	s_cselect_b32 s98, s58, 0
	s_cmp_gt_u32 s98, 1
	s_cbranch_scc1 .Ltw_relax_1027_0
	s_waitcnt vmcnt(8)
	s_branch .Ltw_join_1027_0
.Ltw_relax_1027_0:
	s_waitcnt vmcnt(40)
.Ltw_join_1027_0:
	s_waitcnt lgkmcnt(0)
	s_barrier
	s_setprio 1
	s_waitcnt lgkmcnt(0)
	v_mfma_f32_16x16x32_bf16 v[126:129], v[140:143], v[176:179], v[126:129]
	v_mfma_f32_16x16x32_bf16 v[122:125], v[152:155], v[176:179], v[122:125]
	v_mfma_f32_16x16x32_bf16 v[114:117], v[140:143], v[190:193], v[114:117]
	v_mfma_f32_16x16x32_bf16 v[106:109], v[152:155], v[190:193], v[106:109]
	v_mfma_f32_16x16x32_bf16 v[98:101], v[140:143], v[216:219], v[98:101]
	v_mfma_f32_16x16x32_bf16 v[90:93], v[152:155], v[216:219], v[90:93]
	v_mfma_f32_16x16x32_bf16 v[82:85], v[140:143], v[224:227], v[82:85]
	v_mfma_f32_16x16x32_bf16 v[74:77], v[152:155], v[224:227], v[74:77]
	v_mfma_f32_16x16x32_bf16 v[126:129], v[148:151], v[186:189], v[126:129]
	v_mfma_f32_16x16x32_bf16 v[122:125], v[156:159], v[186:189], v[122:125]
	v_mfma_f32_16x16x32_bf16 v[114:117], v[148:151], v[212:215], v[114:117]
	v_mfma_f32_16x16x32_bf16 v[106:109], v[156:159], v[212:215], v[106:109]
	v_mfma_f32_16x16x32_bf16 v[98:101], v[148:151], v[220:223], v[98:101]
	v_mfma_f32_16x16x32_bf16 v[90:93], v[156:159], v[220:223], v[90:93]
	v_mfma_f32_16x16x32_bf16 v[82:85], v[148:151], v[228:231], v[82:85]
	v_mfma_f32_16x16x32_bf16 v[74:77], v[156:159], v[228:231], v[74:77]
	s_setprio 0
	s_setprio 1
	v_mfma_f32_16x16x32_bf16 v[118:121], v[160:163], v[176:179], v[118:121]
	v_mfma_f32_16x16x32_bf16 v[110:113], v[168:171], v[176:179], v[110:113]
	v_mfma_f32_16x16x32_bf16 v[102:105], v[160:163], v[190:193], v[102:105]
	v_mfma_f32_16x16x32_bf16 v[94:97], v[168:171], v[190:193], v[94:97]
	v_mfma_f32_16x16x32_bf16 v[86:89], v[160:163], v[216:219], v[86:89]
	v_mfma_f32_16x16x32_bf16 v[78:81], v[168:171], v[216:219], v[78:81]
	v_mfma_f32_16x16x32_bf16 v[70:73], v[160:163], v[224:227], v[70:73]
	v_mfma_f32_16x16x32_bf16 v[66:69], v[168:171], v[224:227], v[66:69]
	v_mfma_f32_16x16x32_bf16 v[118:121], v[164:167], v[186:189], v[118:121]
	v_mfma_f32_16x16x32_bf16 v[110:113], v[172:175], v[186:189], v[110:113]
	v_mfma_f32_16x16x32_bf16 v[102:105], v[164:167], v[212:215], v[102:105]
	v_mfma_f32_16x16x32_bf16 v[94:97], v[172:175], v[212:215], v[94:97]
	v_mfma_f32_16x16x32_bf16 v[86:89], v[164:167], v[220:223], v[86:89]
	v_mfma_f32_16x16x32_bf16 v[78:81], v[172:175], v[220:223], v[78:81]
	v_mfma_f32_16x16x32_bf16 v[70:73], v[164:167], v[228:231], v[70:73]
	v_mfma_f32_16x16x32_bf16 v[66:69], v[172:175], v[228:231], v[66:69]
	s_setprio 0
	s_barrier
	s_add_i32 s63, s63, s51
	v_lshl_add_u64 v[180:181], s[26:27], 0, v[0:1]
	s_mov_b32 m0, s63
	ds_read_b128 v[176:179], v147 offset:16384
	ds_read_b128 v[186:189], v147 offset:17408
	ds_read_b128 v[190:193], v147 offset:18432
	ds_read_b128 v[212:215], v147 offset:19456
	ds_read_b128 v[216:219], v147 offset:20480
	ds_read_b128 v[220:223], v147 offset:21504
	ds_read_b128 v[224:227], v147 offset:22528
	ds_read_b128 v[228:231], v147 offset:23552
	global_load_lds_dwordx4 v[180:181], off
	s_add_i32 m0, s63, 0x2000
	s_add_u32 s64, s26, 0x40000
	v_lshl_add_u64 v[194:195], s[26:27], 0, v[134:135]
	s_addc_u32 s65, s27, 0
	s_add_i32 s63, s67, s51
	global_load_lds_dwordx4 v[194:195], off
	v_lshl_add_u64 v[232:233], s[64:65], 0, v[0:1]
	s_mov_b32 m0, s63
	v_lshl_add_u64 v[234:235], s[28:29], 0, v[132:133]
	global_load_lds_dwordx4 v[232:233], off
	v_lshl_add_u64 v[232:233], s[64:65], 0, v[134:135]
	s_add_i32 m0, s63, 0x2000
	s_nop 0
	global_load_lds_dwordx4 v[232:233], off
	v_lshl_add_u64 v[232:233], s[28:29], 0, v[130:131]
	s_mov_b32 m0, s19
	s_nop 0
	global_load_lds_dwordx4 v[232:233], off
	s_mov_b32 m0, s52
	s_nop 0
	global_load_lds_dwordx4 v[234:235], off
	s_cmp_eq_u32 s62, -2
	s_cselect_b32 s98, s58, 0
	s_cmp_gt_u32 s98, 1
	s_cbranch_scc1 .Ltw_relax_1027_1
	s_waitcnt vmcnt(8)
	s_branch .Ltw_join_1027_1

.Ltw_join_1027_1:
	s_waitcnt lgkmcnt(0)
	s_barrier
	s_setprio 1
	s_waitcnt lgkmcnt(0)
	v_mfma_f32_16x16x32_bf16 v[62:65], v[140:143], v[176:179], v[62:65]
	v_mfma_f32_16x16x32_bf16 v[58:61], v[152:155], v[176:179], v[58:61]
	v_mfma_f32_16x16x32_bf16 v[50:53], v[140:143], v[190:193], v[50:53]
	v_mfma_f32_16x16x32_bf16 v[42:45], v[152:155], v[190:193], v[42:45]
	v_mfma_f32_16x16x32_bf16 v[34:37], v[140:143], v[216:219], v[34:37]
	v_mfma_f32_16x16x32_bf16 v[26:29], v[152:155], v[216:219], v[26:29]
	v_mfma_f32_16x16x32_bf16 v[18:21], v[140:143], v[224:227], v[18:21]
	v_mfma_f32_16x16x32_bf16 v[10:13], v[152:155], v[224:227], v[10:13]
	v_mfma_f32_16x16x32_bf16 v[62:65], v[148:151], v[186:189], v[62:65]
	v_mfma_f32_16x16x32_bf16 v[58:61], v[156:159], v[186:189], v[58:61]
	v_mfma_f32_16x16x32_bf16 v[50:53], v[148:151], v[212:215], v[50:53]
	v_mfma_f32_16x16x32_bf16 v[42:45], v[156:159], v[212:215], v[42:45]
	v_mfma_f32_16x16x32_bf16 v[34:37], v[148:151], v[220:223], v[34:37]
	v_mfma_f32_16x16x32_bf16 v[26:29], v[156:159], v[220:223], v[26:29]
	v_mfma_f32_16x16x32_bf16 v[18:21], v[148:151], v[228:231], v[18:21]
	v_mfma_f32_16x16x32_bf16 v[10:13], v[156:159], v[228:231], v[10:13]
	s_setprio 0
	s_setprio 1
	v_mfma_f32_16x16x32_bf16 v[54:57], v[160:163], v[176:179], v[54:57]
	v_mfma_f32_16x16x32_bf16 v[46:49], v[168:171], v[176:179], v[46:49]
	v_mfma_f32_16x16x32_bf16 v[38:41], v[160:163], v[190:193], v[38:41]
	v_mfma_f32_16x16x32_bf16 v[30:33], v[168:171], v[190:193], v[30:33]
	v_mfma_f32_16x16x32_bf16 v[22:25], v[160:163], v[216:219], v[22:25]
	v_mfma_f32_16x16x32_bf16 v[14:17], v[168:171], v[216:219], v[14:17]
	v_mfma_f32_16x16x32_bf16 v[6:9], v[160:163], v[224:227], v[6:9]
	v_mfma_f32_16x16x32_bf16 v[2:5], v[168:171], v[224:227], v[2:5]
	v_mfma_f32_16x16x32_bf16 v[54:57], v[164:167], v[186:189], v[54:57]
	v_mfma_f32_16x16x32_bf16 v[46:49], v[172:175], v[186:189], v[46:49]
	v_mfma_f32_16x16x32_bf16 v[38:41], v[164:167], v[212:215], v[38:41]
	v_mfma_f32_16x16x32_bf16 v[30:33], v[172:175], v[212:215], v[30:33]
	v_mfma_f32_16x16x32_bf16 v[22:25], v[164:167], v[220:223], v[22:25]
	v_mfma_f32_16x16x32_bf16 v[14:17], v[172:175], v[220:223], v[14:17]
	v_mfma_f32_16x16x32_bf16 v[6:9], v[164:167], v[228:231], v[6:9]
	v_mfma_f32_16x16x32_bf16 v[2:5], v[172:175], v[228:231], v[2:5]
	s_setprio 0
	s_barrier
	s_add_i32 s63, 0, 0x18000
	s_add_i32 s64, 0, 0x1c000
	v_add_u32_e32 v156, s63, v145
	v_add_u32_e32 v172, s64, v145
	ds_read_b128 v[140:143], v156
	ds_read_b128 v[148:151], v156 offset:1024
	ds_read_b128 v[152:155], v156 offset:2048
	ds_read_b128 v[156:159], v156 offset:3072
	ds_read_b128 v[160:163], v172
	ds_read_b128 v[164:167], v172 offset:1024
	ds_read_b128 v[168:171], v172 offset:2048
	ds_read_b128 v[172:175], v172 offset:3072
	s_add_u32 s28, s28, 0x40000
	s_addc_u32 s29, s29, 0
	s_mov_b32 m0, s53
	v_lshl_add_u64 v[236:237], s[28:29], 0, v[130:131]
	ds_read_b128 v[176:179], v147 offset:32768
	ds_read_b128 v[186:189], v147 offset:33792
	ds_read_b128 v[190:193], v147 offset:34816
	ds_read_b128 v[212:215], v147 offset:35840
	ds_read_b128 v[216:219], v147 offset:36864
	ds_read_b128 v[220:223], v147 offset:37888
	ds_read_b128 v[224:227], v147 offset:38912
	ds_read_b128 v[228:231], v147 offset:39936
	global_load_lds_dwordx4 v[236:237], off
	v_lshl_add_u64 v[236:237], s[28:29], 0, v[132:133]
	s_mov_b32 m0, s54
	s_nop 0
	global_load_lds_dwordx4 v[236:237], off
	s_waitcnt vmcnt(8)
	s_waitcnt lgkmcnt(0)
	s_barrier
	s_setprio 1
	s_waitcnt lgkmcnt(0)
	v_mfma_f32_16x16x32_bf16 v[126:129], v[140:143], v[176:179], v[126:129]
	v_mfma_f32_16x16x32_bf16 v[122:125], v[152:155], v[176:179], v[122:125]
	v_mfma_f32_16x16x32_bf16 v[114:117], v[140:143], v[190:193], v[114:117]
	v_mfma_f32_16x16x32_bf16 v[106:109], v[152:155], v[190:193], v[106:109]
	v_mfma_f32_16x16x32_bf16 v[98:101], v[140:143], v[216:219], v[98:101]
	v_mfma_f32_16x16x32_bf16 v[90:93], v[152:155], v[216:219], v[90:93]
	v_mfma_f32_16x16x32_bf16 v[82:85], v[140:143], v[224:227], v[82:85]
	v_mfma_f32_16x16x32_bf16 v[74:77], v[152:155], v[224:227], v[74:77]
	v_mfma_f32_16x16x32_bf16 v[126:129], v[148:151], v[186:189], v[126:129]
	v_mfma_f32_16x16x32_bf16 v[122:125], v[156:159], v[186:189], v[122:125]
	v_mfma_f32_16x16x32_bf16 v[114:117], v[148:151], v[212:215], v[114:117]
	v_mfma_f32_16x16x32_bf16 v[106:109], v[156:159], v[212:215], v[106:109]
	v_mfma_f32_16x16x32_bf16 v[98:101], v[148:151], v[220:223], v[98:101]
	v_mfma_f32_16x16x32_bf16 v[90:93], v[156:159], v[220:223], v[90:93]
	v_mfma_f32_16x16x32_bf16 v[82:85], v[148:151], v[228:231], v[82:85]
	v_mfma_f32_16x16x32_bf16 v[74:77], v[156:159], v[228:231], v[74:77]
	s_setprio 0
	s_setprio 1
	v_mfma_f32_16x16x32_bf16 v[118:121], v[160:163], v[176:179], v[118:121]
	v_mfma_f32_16x16x32_bf16 v[110:113], v[168:171], v[176:179], v[110:113]
	v_mfma_f32_16x16x32_bf16 v[102:105], v[160:163], v[190:193], v[102:105]
	v_mfma_f32_16x16x32_bf16 v[94:97], v[168:171], v[190:193], v[94:97]
	v_mfma_f32_16x16x32_bf16 v[86:89], v[160:163], v[216:219], v[86:89]
	v_mfma_f32_16x16x32_bf16 v[78:81], v[168:171], v[216:219], v[78:81]
	v_mfma_f32_16x16x32_bf16 v[70:73], v[160:163], v[224:227], v[70:73]
	v_mfma_f32_16x16x32_bf16 v[66:69], v[168:171], v[224:227], v[66:69]
	v_mfma_f32_16x16x32_bf16 v[118:121], v[164:167], v[186:189], v[118:121]
	v_mfma_f32_16x16x32_bf16 v[110:113], v[172:175], v[186:189], v[110:113]
	v_mfma_f32_16x16x32_bf16 v[102:105], v[164:167], v[212:215], v[102:105]
	v_mfma_f32_16x16x32_bf16 v[94:97], v[172:175], v[212:215], v[94:97]
	v_mfma_f32_16x16x32_bf16 v[86:89], v[164:167], v[220:223], v[86:89]
	v_mfma_f32_16x16x32_bf16 v[78:81], v[172:175], v[220:223], v[78:81]
	v_mfma_f32_16x16x32_bf16 v[70:73], v[164:167], v[228:231], v[70:73]
	v_mfma_f32_16x16x32_bf16 v[66:69], v[172:175], v[228:231], v[66:69]
	s_setprio 0
	s_barrier
	s_add_i32 s28, s63, s51
	v_lshl_add_u64 v[180:181], v[180:181], 0, s[16:17]
	s_mov_b32 m0, s28
	ds_read_b128 v[176:179], v147 offset:49152
	ds_read_b128 v[186:189], v147 offset:50176
	ds_read_b128 v[190:193], v147 offset:51200
	ds_read_b128 v[212:215], v147 offset:52224
	ds_read_b128 v[216:219], v147 offset:53248
	ds_read_b128 v[220:223], v147 offset:54272
	ds_read_b128 v[224:227], v147 offset:55296
	ds_read_b128 v[228:231], v147 offset:56320
	global_load_lds_dwordx4 v[180:181], off
	s_add_i32 m0, s28, 0x2000
	s_add_u32 s26, s26, 0x40080
	v_lshl_add_u64 v[180:181], v[194:195], 0, s[16:17]
	s_addc_u32 s27, s27, 0
	s_add_i32 s28, s64, s51
	global_load_lds_dwordx4 v[180:181], off
	v_lshl_add_u64 v[180:181], s[26:27], 0, v[0:1]
	s_mov_b32 m0, s28
	s_nop 0
	global_load_lds_dwordx4 v[180:181], off
	v_lshl_add_u64 v[180:181], s[26:27], 0, v[134:135]
	s_add_i32 m0, s28, 0x2000
	s_nop 0
	global_load_lds_dwordx4 v[180:181], off
	v_lshl_add_u64 v[180:181], v[232:233], 0, s[16:17]
	s_mov_b32 m0, s56
	s_nop 0
	global_load_lds_dwordx4 v[180:181], off
	v_lshl_add_u64 v[180:181], v[234:235], 0, s[16:17]
	s_mov_b32 m0, s57
	s_nop 0
	global_load_lds_dwordx4 v[180:181], off
	s_waitcnt vmcnt(8)
	s_waitcnt lgkmcnt(0)
	s_barrier
	s_setprio 1
	s_waitcnt lgkmcnt(0)
	v_mfma_f32_16x16x32_bf16 v[62:65], v[140:143], v[176:179], v[62:65]
	v_mfma_f32_16x16x32_bf16 v[58:61], v[152:155], v[176:179], v[58:61]
	v_mfma_f32_16x16x32_bf16 v[50:53], v[140:143], v[190:193], v[50:53]
	v_mfma_f32_16x16x32_bf16 v[42:45], v[152:155], v[190:193], v[42:45]
	v_mfma_f32_16x16x32_bf16 v[34:37], v[140:143], v[216:219], v[34:37]
	v_mfma_f32_16x16x32_bf16 v[26:29], v[152:155], v[216:219], v[26:29]
	v_mfma_f32_16x16x32_bf16 v[18:21], v[140:143], v[224:227], v[18:21]
	v_mfma_f32_16x16x32_bf16 v[10:13], v[152:155], v[224:227], v[10:13]
	v_mfma_f32_16x16x32_bf16 v[62:65], v[148:151], v[186:189], v[62:65]
	v_mfma_f32_16x16x32_bf16 v[58:61], v[156:159], v[186:189], v[58:61]
	v_mfma_f32_16x16x32_bf16 v[50:53], v[148:151], v[212:215], v[50:53]
	v_mfma_f32_16x16x32_bf16 v[42:45], v[156:159], v[212:215], v[42:45]
	v_mfma_f32_16x16x32_bf16 v[34:37], v[148:151], v[220:223], v[34:37]
	v_mfma_f32_16x16x32_bf16 v[26:29], v[156:159], v[220:223], v[26:29]
	v_mfma_f32_16x16x32_bf16 v[18:21], v[148:151], v[228:231], v[18:21]
	v_mfma_f32_16x16x32_bf16 v[10:13], v[156:159], v[228:231], v[10:13]
	s_setprio 0
	s_setprio 1
	v_mfma_f32_16x16x32_bf16 v[54:57], v[160:163], v[176:179], v[54:57]
	v_mfma_f32_16x16x32_bf16 v[46:49], v[168:171], v[176:179], v[46:49]
	v_mfma_f32_16x16x32_bf16 v[38:41], v[160:163], v[190:193], v[38:41]
	v_mfma_f32_16x16x32_bf16 v[30:33], v[168:171], v[190:193], v[30:33]
	v_mfma_f32_16x16x32_bf16 v[22:25], v[160:163], v[216:219], v[22:25]
	v_mfma_f32_16x16x32_bf16 v[14:17], v[168:171], v[216:219], v[14:17]
	v_mfma_f32_16x16x32_bf16 v[6:9], v[160:163], v[224:227], v[6:9]
	v_mfma_f32_16x16x32_bf16 v[2:5], v[168:171], v[224:227], v[2:5]
	v_mfma_f32_16x16x32_bf16 v[54:57], v[164:167], v[186:189], v[54:57]
	v_mfma_f32_16x16x32_bf16 v[46:49], v[172:175], v[186:189], v[46:49]
	v_mfma_f32_16x16x32_bf16 v[38:41], v[164:167], v[212:215], v[38:41]
	v_mfma_f32_16x16x32_bf16 v[30:33], v[172:175], v[212:215], v[30:33]
	v_mfma_f32_16x16x32_bf16 v[22:25], v[164:167], v[220:223], v[22:25]
	v_mfma_f32_16x16x32_bf16 v[14:17], v[172:175], v[220:223], v[14:17]
	v_mfma_f32_16x16x32_bf16 v[6:9], v[164:167], v[228:231], v[6:9]
	v_mfma_f32_16x16x32_bf16 v[2:5], v[172:175], v[228:231], v[2:5]
	s_setprio 0
	s_barrier
	s_add_i32 s62, s62, 2
	s_add_u32 s24, s24, 0x100
	s_addc_u32 s25, s25, 0
	s_add_u32 s60, s60, 0x100
	s_addc_u32 s61, s61, 0
	s_cmp_gt_u32 s62, 13
	s_cbranch_scc0 .LBB0_1027
	s_and_b64 vcc, exec, s[8:9]
	s_cbranch_vccz .LBB0_1030
	s_barrier
